# GEMM engine: counted LDS waits inside the MFMA cluster (lgkmcnt 7/5/3/1/0) instead of one full wait
# speedup vs baseline: 1.0124x; 1.0048x over previous
; #define PG8_STAGE(bufoff, gbase, voff) do { _Pragma("unroll") for (int _i = 0; _i < 2; ++_i) \
;         __builtin_amdgcn_global_load_lds((const unsigned*)((const char*)(gbase) + (voff)[_i]), (LAS unsigned*)(lds + (bufoff) + ldsw + _i * 8192), 16, 0, 0); } while (0)
; #define PG8_LDA(dst, b, h) do { _Pragma("unroll") for (int m = 0; m < 4; ++m) _Pragma("unroll") for (int k = 0; k < 2; ++k) dst[m][k] = *(const LAS bf16x8*)(lds + PG8_SA(b, h) + aoff + m * 2048 + k * 1024); } while (0)
; #define PG8_LDB(dst, b, h) do { _Pragma("unroll") for (int n = 0; n < 2; ++n) _Pragma("unroll") for (int k = 0; k < 2; ++k) dst[n][k] = *(const LAS bf16x8*)(lds + PG8_SB(b, h) + boff + n * 2048 + k * 1024); } while (0)
; #define PG8_WAIT_V(n) asm volatile("s_waitcnt vmcnt(" #n ")" ::: "memory")
; #define PG8_WAIT_L(n) asm volatile("s_waitcnt lgkmcnt(" #n ")" ::: "memory")
; __device__ __forceinline__ void gemm_phase(LAS unsigned char* lds, const Desc& g, int G, int cidx, int tid) {
;     ...
;         for (int t = 0; t < nt; t += 2) {
;             const bool last = (t == nt - 2);
;             const char* a1 = cA + (size_t)(t + 1) * kstep;
;             const char* a2 = last ? nA : cA + (size_t)(t + 2) * kstep; const char* b2 = last ? nB : cB + (size_t)(t + 2) * kstep;
;             const char* a3 = a2 + kstep; const char* b3 = b2 + kstep;
;             PG8_LDB(B0, 0, 0); PG8_LDB(B1, 0, 1); PG8_SCHED; PG8_LDA(At, 0, 0); PG8_STAGE(PG8_SA(1, 1), a1 + hstepA, voffA);
;             PG8_WAIT_V(8); PG8_WAIT_L(0); PG8_BAR; PG8_MMA(0, 0, At, B0); PG8_MMA(0, 1, At, B1); PG8_BAR; PG8_SCHED;
;             PG8_LDA(At, 0, 1); PG8_STAGE(PG8_SB(0, 0), b2, voffB); PG8_STAGE(PG8_SB(0, 1), b2 + hstepB, voffB); PG8_STAGE(PG8_SA(0, 0), a2, voffA);
;             PG8_WAIT_V(8); PG8_WAIT_L(0); PG8_BAR; PG8_MMA(1, 0, At, B0); PG8_MMA(1, 1, At, B1); PG8_BAR; PG8_SCHED;
;             PG8_LDB(B0, 1, 0); PG8_LDB(B1, 1, 1); PG8_SCHED; PG8_LDA(At, 1, 0); PG8_STAGE(PG8_SA(0, 1), a2 + hstepA, voffA);
;             PG8_WAIT_V(8); PG8_WAIT_L(0); PG8_BAR; PG8_MMA(0, 0, At, B0); PG8_MMA(0, 1, At, B1); PG8_BAR; PG8_SCHED;
;             PG8_LDA(At, 1, 1); PG8_STAGE(PG8_SB(1, 0), b3, voffB); PG8_STAGE(PG8_SB(1, 1), b3 + hstepB, voffB); PG8_STAGE(PG8_SA(1, 0), a3, voffA);
;             PG8_WAIT_V(8); PG8_WAIT_L(0); PG8_BAR; PG8_MMA(1, 0, At, B0); PG8_MMA(1, 1, At, B1); PG8_BAR; PG8_SCHED;
;         }
.LBB0_199:
	s_add_u32 s52, s50, 0x100
	s_addc_u32 s53, s51, 0
	s_add_i32 s42, 0, 0x10000
	s_cmp_eq_u32 s63, 62
	s_cselect_b32 s59, s1, s53
	s_cselect_b32 s58, s0, s52
	v_add_u32_e32 v142, s42, v139
	s_cselect_b32 s57, s49, s62
	s_cselect_b32 s56, s48, s61
	s_add_i32 s43, 0, 0x14000
	ds_read_b128 v[156:159], v142
	ds_read_b128 v[160:163], v142 offset:1024
	ds_read_b128 v[164:167], v142 offset:2048
	ds_read_b128 v[168:171], v142 offset:3072
	v_add_u32_e32 v142, s43, v139
	ds_read_b128 v[172:175], v142
	ds_read_b128 v[176:179], v142 offset:1024
	ds_read_b128 v[180:183], v142 offset:2048
	ds_read_b128 v[184:187], v142 offset:3072
	v_lshl_add_u64 v[142:143], s[50:51], 0, v[136:137]
	s_add_i32 m0, s7, 0xc000
	ds_read_b128 v[188:191], v141
	ds_read_b128 v[192:195], v141 offset:1024
	ds_read_b128 v[196:199], v141 offset:2048
	ds_read_b128 v[206:209], v141 offset:3072
	ds_read_b128 v[210:213], v141 offset:4096
	ds_read_b128 v[214:217], v141 offset:5120
	ds_read_b128 v[218:221], v141 offset:6144
	ds_read_b128 v[222:225], v141 offset:7168
	global_load_lds_dwordx4 v[142:143], off
	v_lshl_add_u64 v[142:143], s[50:51], 0, v[134:135]
	s_add_i32 m0, s7, 0xe000
	s_nop 0
	global_load_lds_dwordx4 v[142:143], off
	s_waitcnt vmcnt(8)
	s_barrier
	s_setprio 1
	s_waitcnt lgkmcnt(7)
	v_mfma_f32_16x16x32_bf16 v[124:127], v[156:159], v[188:191], v[124:127]
	v_mfma_f32_16x16x32_bf16 v[120:123], v[164:167], v[188:191], v[120:123]
	s_waitcnt lgkmcnt(5)
	v_mfma_f32_16x16x32_bf16 v[108:111], v[156:159], v[196:199], v[108:111]
	v_mfma_f32_16x16x32_bf16 v[104:107], v[164:167], v[196:199], v[104:107]
	s_waitcnt lgkmcnt(3)
	v_mfma_f32_16x16x32_bf16 v[92:95], v[156:159], v[210:213], v[92:95]
	v_mfma_f32_16x16x32_bf16 v[88:91], v[164:167], v[210:213], v[88:91]
	s_waitcnt lgkmcnt(1)
	v_mfma_f32_16x16x32_bf16 v[76:79], v[156:159], v[218:221], v[76:79]
	v_mfma_f32_16x16x32_bf16 v[72:75], v[164:167], v[218:221], v[72:75]
	v_mfma_f32_16x16x32_bf16 v[124:127], v[160:163], v[192:195], v[124:127]
	v_mfma_f32_16x16x32_bf16 v[120:123], v[168:171], v[192:195], v[120:123]
	v_mfma_f32_16x16x32_bf16 v[108:111], v[160:163], v[206:209], v[108:111]
	v_mfma_f32_16x16x32_bf16 v[104:107], v[168:171], v[206:209], v[104:107]
	v_mfma_f32_16x16x32_bf16 v[92:95], v[160:163], v[214:217], v[92:95]
	v_mfma_f32_16x16x32_bf16 v[88:91], v[168:171], v[214:217], v[88:91]
	s_waitcnt lgkmcnt(0)
	v_mfma_f32_16x16x32_bf16 v[76:79], v[160:163], v[222:225], v[76:79]
	v_mfma_f32_16x16x32_bf16 v[72:75], v[168:171], v[222:225], v[72:75]
	s_setprio 0
	s_setprio 1
	v_mfma_f32_16x16x32_bf16 v[116:119], v[172:175], v[188:191], v[116:119]
	v_mfma_f32_16x16x32_bf16 v[112:115], v[180:183], v[188:191], v[112:115]
	v_mfma_f32_16x16x32_bf16 v[100:103], v[172:175], v[196:199], v[100:103]
	v_mfma_f32_16x16x32_bf16 v[96:99], v[180:183], v[196:199], v[96:99]
	v_mfma_f32_16x16x32_bf16 v[84:87], v[172:175], v[210:213], v[84:87]
	v_mfma_f32_16x16x32_bf16 v[80:83], v[180:183], v[210:213], v[80:83]
	v_mfma_f32_16x16x32_bf16 v[68:71], v[172:175], v[218:221], v[68:71]
	v_mfma_f32_16x16x32_bf16 v[64:67], v[180:183], v[218:221], v[64:67]
	v_mfma_f32_16x16x32_bf16 v[116:119], v[176:179], v[192:195], v[116:119]
	v_mfma_f32_16x16x32_bf16 v[112:115], v[184:187], v[192:195], v[112:115]
	v_mfma_f32_16x16x32_bf16 v[100:103], v[176:179], v[206:209], v[100:103]
	v_mfma_f32_16x16x32_bf16 v[96:99], v[184:187], v[206:209], v[96:99]
	v_mfma_f32_16x16x32_bf16 v[84:87], v[176:179], v[214:217], v[84:87]
	v_mfma_f32_16x16x32_bf16 v[80:83], v[184:187], v[214:217], v[80:83]
	v_mfma_f32_16x16x32_bf16 v[68:71], v[176:179], v[222:225], v[68:71]
	v_mfma_f32_16x16x32_bf16 v[64:67], v[184:187], v[222:225], v[64:67]
	s_setprio 0
	s_barrier
	s_add_i32 s42, s42, s6
	v_lshl_add_u64 v[142:143], s[56:57], 0, v[144:145]
	s_mov_b32 m0, s42
	ds_read_b128 v[188:191], v141 offset:16384
	ds_read_b128 v[192:195], v141 offset:17408
	ds_read_b128 v[196:199], v141 offset:18432
	ds_read_b128 v[206:209], v141 offset:19456
	ds_read_b128 v[210:213], v141 offset:20480
	ds_read_b128 v[214:217], v141 offset:21504
	ds_read_b128 v[218:221], v141 offset:22528
	ds_read_b128 v[222:225], v141 offset:23552
	global_load_lds_dwordx4 v[142:143], off
	s_add_i32 m0, s42, 0x2000
	s_add_u32 s50, s56, 0x110000
	v_lshl_add_u64 v[146:147], s[56:57], 0, v[128:129]
	s_addc_u32 s51, s57, 0
	s_add_i32 s42, s43, s6
	global_load_lds_dwordx4 v[146:147], off
	v_lshl_add_u64 v[148:149], s[50:51], 0, v[144:145]
	s_mov_b32 m0, s42
	v_lshl_add_u64 v[200:201], s[58:59], 0, v[130:131]
	global_load_lds_dwordx4 v[148:149], off
	v_lshl_add_u64 v[148:149], s[50:51], 0, v[128:129]
	s_add_i32 m0, s42, 0x2000
	s_nop 0
	global_load_lds_dwordx4 v[148:149], off
	v_lshl_add_u64 v[148:149], s[58:59], 0, v[132:133]
	s_mov_b32 m0, s7
	s_nop 0
	global_load_lds_dwordx4 v[148:149], off
	s_mov_b32 m0, s13
	s_nop 0
	global_load_lds_dwordx4 v[200:201], off
	s_waitcnt vmcnt(8)
	s_barrier
; #define PG8_STAGE(bufoff, gbase, voff) do { _Pragma("unroll") for (int _i = 0; _i < 2; ++_i) \
;         __builtin_amdgcn_global_load_lds((const unsigned*)((const char*)(gbase) + (voff)[_i]), (LAS unsigned*)(lds + (bufoff) + ldsw + _i * 8192), 16, 0, 0); } while (0)
; #define PG8_LDA(dst, b, h) do { _Pragma("unroll") for (int m = 0; m < 4; ++m) _Pragma("unroll") for (int k = 0; k < 2; ++k) dst[m][k] = *(const LAS bf16x8*)(lds + PG8_SA(b, h) + aoff + m * 2048 + k * 1024); } while (0)
; #define PG8_LDB(dst, b, h) do { _Pragma("unroll") for (int n = 0; n < 2; ++n) _Pragma("unroll") for (int k = 0; k < 2; ++k) dst[n][k] = *(const LAS bf16x8*)(lds + PG8_SB(b, h) + boff + n * 2048 + k * 1024); } while (0)
; #define PG8_WAIT_V(n) asm volatile("s_waitcnt vmcnt(" #n ")" ::: "memory")
; #define PG8_WAIT_L(n) asm volatile("s_waitcnt lgkmcnt(" #n ")" ::: "memory")
; __device__ __forceinline__ void gemm_phase(LAS unsigned char* lds, const Desc& g, int G, int cidx, int tid) {
;     ...
;         for (int t = 0; t < nt; t += 2) {
;             const bool last = (t == nt - 2);
;             const char* a1 = cA + (size_t)(t + 1) * kstep;
;             const char* a2 = last ? nA : cA + (size_t)(t + 2) * kstep; const char* b2 = last ? nB : cB + (size_t)(t + 2) * kstep;
;             const char* a3 = a2 + kstep; const char* b3 = b2 + kstep;
;             PG8_LDB(B0, 0, 0); PG8_LDB(B1, 0, 1); PG8_SCHED; PG8_LDA(At, 0, 0); PG8_STAGE(PG8_SA(1, 1), a1 + hstepA, voffA);
;             PG8_WAIT_V(8); PG8_WAIT_L(0); PG8_BAR; PG8_MMA(0, 0, At, B0); PG8_MMA(0, 1, At, B1); PG8_BAR; PG8_SCHED;
;             PG8_LDA(At, 0, 1); PG8_STAGE(PG8_SB(0, 0), b2, voffB); PG8_STAGE(PG8_SB(0, 1), b2 + hstepB, voffB); PG8_STAGE(PG8_SA(0, 0), a2, voffA);
;             PG8_WAIT_V(8); PG8_WAIT_L(0); PG8_BAR; PG8_MMA(1, 0, At, B0); PG8_MMA(1, 1, At, B1); PG8_BAR; PG8_SCHED;
;             PG8_LDB(B0, 1, 0); PG8_LDB(B1, 1, 1); PG8_SCHED; PG8_LDA(At, 1, 0); PG8_STAGE(PG8_SA(0, 1), a2 + hstepA, voffA);
;             PG8_WAIT_V(8); PG8_WAIT_L(0); PG8_BAR; PG8_MMA(0, 0, At, B0); PG8_MMA(0, 1, At, B1); PG8_BAR; PG8_SCHED;
;             PG8_LDA(At, 1, 1); PG8_STAGE(PG8_SB(1, 0), b3, voffB); PG8_STAGE(PG8_SB(1, 1), b3 + hstepB, voffB); PG8_STAGE(PG8_SA(1, 0), a3, voffA);
;             PG8_WAIT_V(8); PG8_WAIT_L(0); PG8_BAR; PG8_MMA(1, 0, At, B0); PG8_MMA(1, 1, At, B1); PG8_BAR; PG8_SCHED;
;         }
	s_setprio 1
	s_waitcnt lgkmcnt(7)
	v_mfma_f32_16x16x32_bf16 v[60:63], v[156:159], v[188:191], v[60:63]
	v_mfma_f32_16x16x32_bf16 v[56:59], v[164:167], v[188:191], v[56:59]
	s_waitcnt lgkmcnt(5)
	v_mfma_f32_16x16x32_bf16 v[44:47], v[156:159], v[196:199], v[44:47]
	v_mfma_f32_16x16x32_bf16 v[40:43], v[164:167], v[196:199], v[40:43]
	s_waitcnt lgkmcnt(3)
	v_mfma_f32_16x16x32_bf16 v[28:31], v[156:159], v[210:213], v[28:31]
	v_mfma_f32_16x16x32_bf16 v[24:27], v[164:167], v[210:213], v[24:27]
	s_waitcnt lgkmcnt(1)
	v_mfma_f32_16x16x32_bf16 v[12:15], v[156:159], v[218:221], v[12:15]
	v_mfma_f32_16x16x32_bf16 v[8:11], v[164:167], v[218:221], v[8:11]
	v_mfma_f32_16x16x32_bf16 v[60:63], v[160:163], v[192:195], v[60:63]
	v_mfma_f32_16x16x32_bf16 v[56:59], v[168:171], v[192:195], v[56:59]
	v_mfma_f32_16x16x32_bf16 v[44:47], v[160:163], v[206:209], v[44:47]
	v_mfma_f32_16x16x32_bf16 v[40:43], v[168:171], v[206:209], v[40:43]
	v_mfma_f32_16x16x32_bf16 v[28:31], v[160:163], v[214:217], v[28:31]
	v_mfma_f32_16x16x32_bf16 v[24:27], v[168:171], v[214:217], v[24:27]
	s_waitcnt lgkmcnt(0)
	v_mfma_f32_16x16x32_bf16 v[12:15], v[160:163], v[222:225], v[12:15]
	v_mfma_f32_16x16x32_bf16 v[8:11], v[168:171], v[222:225], v[8:11]
	s_setprio 0
	s_setprio 1
	v_mfma_f32_16x16x32_bf16 v[52:55], v[172:175], v[188:191], v[52:55]
	v_mfma_f32_16x16x32_bf16 v[48:51], v[180:183], v[188:191], v[48:51]
	v_mfma_f32_16x16x32_bf16 v[36:39], v[172:175], v[196:199], v[36:39]
	v_mfma_f32_16x16x32_bf16 v[32:35], v[180:183], v[196:199], v[32:35]
	v_mfma_f32_16x16x32_bf16 v[20:23], v[172:175], v[210:213], v[20:23]
	v_mfma_f32_16x16x32_bf16 v[16:19], v[180:183], v[210:213], v[16:19]
	v_mfma_f32_16x16x32_bf16 v[0:3], v[172:175], v[218:221], v[0:3]
	v_mfma_f32_16x16x32_bf16 v[4:7], v[180:183], v[218:221], v[4:7]
	v_mfma_f32_16x16x32_bf16 v[52:55], v[176:179], v[192:195], v[52:55]
	v_mfma_f32_16x16x32_bf16 v[48:51], v[184:187], v[192:195], v[48:51]
	v_mfma_f32_16x16x32_bf16 v[36:39], v[176:179], v[206:209], v[36:39]
	v_mfma_f32_16x16x32_bf16 v[32:35], v[184:187], v[206:209], v[32:35]
	v_mfma_f32_16x16x32_bf16 v[20:23], v[176:179], v[214:217], v[20:23]
	v_mfma_f32_16x16x32_bf16 v[16:19], v[184:187], v[214:217], v[16:19]
	v_mfma_f32_16x16x32_bf16 v[0:3], v[176:179], v[222:225], v[0:3]
	v_mfma_f32_16x16x32_bf16 v[4:7], v[184:187], v[222:225], v[4:7]
	s_setprio 0
	s_barrier
	s_add_i32 s42, 0, 0x18000
	v_add_u32_e32 v155, s42, v139
	s_add_i32 s43, 0, 0x1c000
	ds_read_b128 v[156:159], v155
	ds_read_b128 v[160:163], v155 offset:1024
	ds_read_b128 v[164:167], v155 offset:2048
	ds_read_b128 v[168:171], v155 offset:3072
	v_add_u32_e32 v155, s43, v139
	ds_read_b128 v[172:175], v155
	ds_read_b128 v[176:179], v155 offset:1024
	ds_read_b128 v[180:183], v155 offset:2048
	ds_read_b128 v[184:187], v155 offset:3072
	s_add_u32 s50, s58, 0x110000
	s_addc_u32 s51, s59, 0
	s_mov_b32 m0, s18
	v_lshl_add_u64 v[226:227], s[50:51], 0, v[132:133]
	ds_read_b128 v[188:191], v141 offset:32768
	ds_read_b128 v[192:195], v141 offset:33792
	ds_read_b128 v[196:199], v141 offset:34816
	ds_read_b128 v[206:209], v141 offset:35840
	ds_read_b128 v[210:213], v141 offset:36864
	ds_read_b128 v[214:217], v141 offset:37888
	ds_read_b128 v[218:221], v141 offset:38912
	ds_read_b128 v[222:225], v141 offset:39936
	global_load_lds_dwordx4 v[226:227], off
	v_lshl_add_u64 v[226:227], s[50:51], 0, v[130:131]
	s_mov_b32 m0, s24
	s_nop 0
	global_load_lds_dwordx4 v[226:227], off
	s_waitcnt vmcnt(8)
	s_barrier
	s_setprio 1
	s_waitcnt lgkmcnt(7)
	v_mfma_f32_16x16x32_bf16 v[124:127], v[156:159], v[188:191], v[124:127]
	v_mfma_f32_16x16x32_bf16 v[120:123], v[164:167], v[188:191], v[120:123]
	s_waitcnt lgkmcnt(5)
	v_mfma_f32_16x16x32_bf16 v[108:111], v[156:159], v[196:199], v[108:111]
	v_mfma_f32_16x16x32_bf16 v[104:107], v[164:167], v[196:199], v[104:107]
	s_waitcnt lgkmcnt(3)
	v_mfma_f32_16x16x32_bf16 v[92:95], v[156:159], v[210:213], v[92:95]
	v_mfma_f32_16x16x32_bf16 v[88:91], v[164:167], v[210:213], v[88:91]
	s_waitcnt lgkmcnt(1)
	v_mfma_f32_16x16x32_bf16 v[76:79], v[156:159], v[218:221], v[76:79]
	v_mfma_f32_16x16x32_bf16 v[72:75], v[164:167], v[218:221], v[72:75]
	v_mfma_f32_16x16x32_bf16 v[124:127], v[160:163], v[192:195], v[124:127]
	v_mfma_f32_16x16x32_bf16 v[120:123], v[168:171], v[192:195], v[120:123]
	v_mfma_f32_16x16x32_bf16 v[108:111], v[160:163], v[206:209], v[108:111]
	v_mfma_f32_16x16x32_bf16 v[104:107], v[168:171], v[206:209], v[104:107]
	v_mfma_f32_16x16x32_bf16 v[92:95], v[160:163], v[214:217], v[92:95]
	v_mfma_f32_16x16x32_bf16 v[88:91], v[168:171], v[214:217], v[88:91]
	s_waitcnt lgkmcnt(0)
	v_mfma_f32_16x16x32_bf16 v[76:79], v[160:163], v[222:225], v[76:79]
	v_mfma_f32_16x16x32_bf16 v[72:75], v[168:171], v[222:225], v[72:75]
	s_setprio 0
	s_setprio 1
	v_mfma_f32_16x16x32_bf16 v[116:119], v[172:175], v[188:191], v[116:119]
	v_mfma_f32_16x16x32_bf16 v[112:115], v[180:183], v[188:191], v[112:115]
	v_mfma_f32_16x16x32_bf16 v[100:103], v[172:175], v[196:199], v[100:103]
	v_mfma_f32_16x16x32_bf16 v[96:99], v[180:183], v[196:199], v[96:99]
	v_mfma_f32_16x16x32_bf16 v[84:87], v[172:175], v[210:213], v[84:87]
	v_mfma_f32_16x16x32_bf16 v[80:83], v[180:183], v[210:213], v[80:83]
	v_mfma_f32_16x16x32_bf16 v[68:71], v[172:175], v[218:221], v[68:71]
	v_mfma_f32_16x16x32_bf16 v[64:67], v[180:183], v[218:221], v[64:67]
	v_mfma_f32_16x16x32_bf16 v[116:119], v[176:179], v[192:195], v[116:119]
	v_mfma_f32_16x16x32_bf16 v[112:115], v[184:187], v[192:195], v[112:115]
	v_mfma_f32_16x16x32_bf16 v[100:103], v[176:179], v[206:209], v[100:103]
	v_mfma_f32_16x16x32_bf16 v[96:99], v[184:187], v[206:209], v[96:99]
	v_mfma_f32_16x16x32_bf16 v[84:87], v[176:179], v[214:217], v[84:87]
	v_mfma_f32_16x16x32_bf16 v[80:83], v[184:187], v[214:217], v[80:83]
	v_mfma_f32_16x16x32_bf16 v[68:71], v[176:179], v[222:225], v[68:71]
	v_mfma_f32_16x16x32_bf16 v[64:67], v[184:187], v[222:225], v[64:67]
	s_setprio 0
	s_barrier
; #define PG8_STAGE(bufoff, gbase, voff) do { _Pragma("unroll") for (int _i = 0; _i < 2; ++_i) \
;         __builtin_amdgcn_global_load_lds((const unsigned*)((const char*)(gbase) + (voff)[_i]), (LAS unsigned*)(lds + (bufoff) + ldsw + _i * 8192), 16, 0, 0); } while (0)
; #define PG8_LDA(dst, b, h) do { _Pragma("unroll") for (int m = 0; m < 4; ++m) _Pragma("unroll") for (int k = 0; k < 2; ++k) dst[m][k] = *(const LAS bf16x8*)(lds + PG8_SA(b, h) + aoff + m * 2048 + k * 1024); } while (0)
; #define PG8_LDB(dst, b, h) do { _Pragma("unroll") for (int n = 0; n < 2; ++n) _Pragma("unroll") for (int k = 0; k < 2; ++k) dst[n][k] = *(const LAS bf16x8*)(lds + PG8_SB(b, h) + boff + n * 2048 + k * 1024); } while (0)
; #define PG8_WAIT_V(n) asm volatile("s_waitcnt vmcnt(" #n ")" ::: "memory")
; #define PG8_WAIT_L(n) asm volatile("s_waitcnt lgkmcnt(" #n ")" ::: "memory")
; __device__ __forceinline__ void gemm_phase(LAS unsigned char* lds, const Desc& g, int G, int cidx, int tid) {
;     ...
;         for (int t = 0; t < nt; t += 2) {
;             const bool last = (t == nt - 2);
;             const char* a1 = cA + (size_t)(t + 1) * kstep;
;             const char* a2 = last ? nA : cA + (size_t)(t + 2) * kstep; const char* b2 = last ? nB : cB + (size_t)(t + 2) * kstep;
;             const char* a3 = a2 + kstep; const char* b3 = b2 + kstep;
;             PG8_LDB(B0, 0, 0); PG8_LDB(B1, 0, 1); PG8_SCHED; PG8_LDA(At, 0, 0); PG8_STAGE(PG8_SA(1, 1), a1 + hstepA, voffA);
;             PG8_WAIT_V(8); PG8_WAIT_L(0); PG8_BAR; PG8_MMA(0, 0, At, B0); PG8_MMA(0, 1, At, B1); PG8_BAR; PG8_SCHED;
;             PG8_LDA(At, 0, 1); PG8_STAGE(PG8_SB(0, 0), b2, voffB); PG8_STAGE(PG8_SB(0, 1), b2 + hstepB, voffB); PG8_STAGE(PG8_SA(0, 0), a2, voffA);
;             PG8_WAIT_V(8); PG8_WAIT_L(0); PG8_BAR; PG8_MMA(1, 0, At, B0); PG8_MMA(1, 1, At, B1); PG8_BAR; PG8_SCHED;
;             PG8_LDB(B0, 1, 0); PG8_LDB(B1, 1, 1); PG8_SCHED; PG8_LDA(At, 1, 0); PG8_STAGE(PG8_SA(0, 1), a2 + hstepA, voffA);
;             PG8_WAIT_V(8); PG8_WAIT_L(0); PG8_BAR; PG8_MMA(0, 0, At, B0); PG8_MMA(0, 1, At, B1); PG8_BAR; PG8_SCHED;
;             PG8_LDA(At, 1, 1); PG8_STAGE(PG8_SB(1, 0), b3, voffB); PG8_STAGE(PG8_SB(1, 1), b3 + hstepB, voffB); PG8_STAGE(PG8_SA(1, 0), a3, voffA);
;             PG8_WAIT_V(8); PG8_WAIT_L(0); PG8_BAR; PG8_MMA(1, 0, At, B0); PG8_MMA(1, 1, At, B1); PG8_BAR; PG8_SCHED;
;         }
	s_add_i32 s42, s42, s6
	v_lshl_add_u64 v[142:143], v[142:143], 0, s[22:23]
	s_mov_b32 m0, s42
	ds_read_b128 v[188:191], v141 offset:49152
	ds_read_b128 v[192:195], v141 offset:50176
	ds_read_b128 v[196:199], v141 offset:51200
	ds_read_b128 v[206:209], v141 offset:52224
	ds_read_b128 v[210:213], v141 offset:53248
	ds_read_b128 v[214:217], v141 offset:54272
	ds_read_b128 v[218:221], v141 offset:55296
	ds_read_b128 v[222:225], v141 offset:56320
	global_load_lds_dwordx4 v[142:143], off
	s_add_i32 m0, s42, 0x2000
	s_add_u32 s50, s56, 0x110080
	v_lshl_add_u64 v[142:143], v[146:147], 0, s[22:23]
	s_addc_u32 s51, s57, 0
	s_add_i32 s42, s43, s6
	global_load_lds_dwordx4 v[142:143], off
	v_lshl_add_u64 v[142:143], s[50:51], 0, v[144:145]
	s_mov_b32 m0, s42
	s_nop 0
	global_load_lds_dwordx4 v[142:143], off
	v_lshl_add_u64 v[142:143], s[50:51], 0, v[128:129]
	s_add_i32 m0, s42, 0x2000
	s_nop 0
	global_load_lds_dwordx4 v[142:143], off
	v_lshl_add_u64 v[142:143], v[148:149], 0, s[22:23]
	s_mov_b32 m0, s26
	s_nop 0
	global_load_lds_dwordx4 v[142:143], off
	v_lshl_add_u64 v[142:143], v[200:201], 0, s[22:23]
	s_mov_b32 m0, s28
	s_nop 0
	global_load_lds_dwordx4 v[142:143], off
	s_waitcnt vmcnt(8)
	s_barrier
	s_setprio 1
	s_waitcnt lgkmcnt(7)
	v_mfma_f32_16x16x32_bf16 v[60:63], v[156:159], v[188:191], v[60:63]
	v_mfma_f32_16x16x32_bf16 v[56:59], v[164:167], v[188:191], v[56:59]
	s_waitcnt lgkmcnt(5)
	v_mfma_f32_16x16x32_bf16 v[44:47], v[156:159], v[196:199], v[44:47]
	v_mfma_f32_16x16x32_bf16 v[40:43], v[164:167], v[196:199], v[40:43]
	s_waitcnt lgkmcnt(3)
	v_mfma_f32_16x16x32_bf16 v[28:31], v[156:159], v[210:213], v[28:31]
	v_mfma_f32_16x16x32_bf16 v[24:27], v[164:167], v[210:213], v[24:27]
	s_waitcnt lgkmcnt(1)
	v_mfma_f32_16x16x32_bf16 v[12:15], v[156:159], v[218:221], v[12:15]
	v_mfma_f32_16x16x32_bf16 v[8:11], v[164:167], v[218:221], v[8:11]
	v_mfma_f32_16x16x32_bf16 v[60:63], v[160:163], v[192:195], v[60:63]
	v_mfma_f32_16x16x32_bf16 v[56:59], v[168:171], v[192:195], v[56:59]
	v_mfma_f32_16x16x32_bf16 v[44:47], v[160:163], v[206:209], v[44:47]
	v_mfma_f32_16x16x32_bf16 v[40:43], v[168:171], v[206:209], v[40:43]
	v_mfma_f32_16x16x32_bf16 v[28:31], v[160:163], v[214:217], v[28:31]
	v_mfma_f32_16x16x32_bf16 v[24:27], v[168:171], v[214:217], v[24:27]
	s_waitcnt lgkmcnt(0)
	v_mfma_f32_16x16x32_bf16 v[12:15], v[160:163], v[222:225], v[12:15]
	v_mfma_f32_16x16x32_bf16 v[8:11], v[168:171], v[222:225], v[8:11]
	s_setprio 0
	s_setprio 1
	v_mfma_f32_16x16x32_bf16 v[52:55], v[172:175], v[188:191], v[52:55]
	v_mfma_f32_16x16x32_bf16 v[48:51], v[180:183], v[188:191], v[48:51]
	v_mfma_f32_16x16x32_bf16 v[36:39], v[172:175], v[196:199], v[36:39]
	v_mfma_f32_16x16x32_bf16 v[32:35], v[180:183], v[196:199], v[32:35]
	v_mfma_f32_16x16x32_bf16 v[20:23], v[172:175], v[210:213], v[20:23]
	v_mfma_f32_16x16x32_bf16 v[16:19], v[180:183], v[210:213], v[16:19]
	v_mfma_f32_16x16x32_bf16 v[0:3], v[172:175], v[218:221], v[0:3]
	v_mfma_f32_16x16x32_bf16 v[4:7], v[180:183], v[218:221], v[4:7]
	v_mfma_f32_16x16x32_bf16 v[52:55], v[176:179], v[192:195], v[52:55]
	v_mfma_f32_16x16x32_bf16 v[48:51], v[184:187], v[192:195], v[48:51]
	v_mfma_f32_16x16x32_bf16 v[36:39], v[176:179], v[206:209], v[36:39]
	v_mfma_f32_16x16x32_bf16 v[32:35], v[184:187], v[206:209], v[32:35]
	v_mfma_f32_16x16x32_bf16 v[20:23], v[176:179], v[214:217], v[20:23]
	v_mfma_f32_16x16x32_bf16 v[16:19], v[184:187], v[214:217], v[16:19]
	v_mfma_f32_16x16x32_bf16 v[0:3], v[176:179], v[222:225], v[0:3]
	v_mfma_f32_16x16x32_bf16 v[4:7], v[184:187], v[222:225], v[4:7]
	s_setprio 0
	s_barrier
	s_add_i32 s63, s63, 2
	s_add_u32 s61, s61, 0x100
	s_addc_u32 s62, s62, 0
	s_cmp_gt_u32 s63, 63
	s_mov_b64 s[50:51], s[52:53]
	s_cbranch_scc0 .LBB0_199
	s_and_b64 vcc, exec, s[36:37]
	s_cbranch_vccz .LBB0_202
	s_barrier

; #define PG8_STAGE(bufoff, gbase, voff) do { _Pragma("unroll") for (int _i = 0; _i < 2; ++_i) \
;         __builtin_amdgcn_global_load_lds((const unsigned*)((const char*)(gbase) + (voff)[_i]), (LAS unsigned*)(lds + (bufoff) + ldsw + _i * 8192), 16, 0, 0); } while (0)
; #define PG8_LDA(dst, b, h) do { _Pragma("unroll") for (int m = 0; m < 4; ++m) _Pragma("unroll") for (int k = 0; k < 2; ++k) dst[m][k] = *(const LAS bf16x8*)(lds + PG8_SA(b, h) + aoff + m * 2048 + k * 1024); } while (0)
; #define PG8_LDB(dst, b, h) do { _Pragma("unroll") for (int n = 0; n < 2; ++n) _Pragma("unroll") for (int k = 0; k < 2; ++k) dst[n][k] = *(const LAS bf16x8*)(lds + PG8_SB(b, h) + boff + n * 2048 + k * 1024); } while (0)
; #define PG8_WAIT_V(n) asm volatile("s_waitcnt vmcnt(" #n ")" ::: "memory")
; #define PG8_WAIT_L(n) asm volatile("s_waitcnt lgkmcnt(" #n ")" ::: "memory")
; __device__ __forceinline__ void gemm_phase(LAS unsigned char* lds, const Desc& g, int G, int cidx, int tid) {
;     ...
;         for (int t = 0; t < nt; t += 2) {
;             const bool last = (t == nt - 2);
;             const char* a1 = cA + (size_t)(t + 1) * kstep;
;             const char* a2 = last ? nA : cA + (size_t)(t + 2) * kstep; const char* b2 = last ? nB : cB + (size_t)(t + 2) * kstep;
;             const char* a3 = a2 + kstep; const char* b3 = b2 + kstep;
;             PG8_LDB(B0, 0, 0); PG8_LDB(B1, 0, 1); PG8_SCHED; PG8_LDA(At, 0, 0); PG8_STAGE(PG8_SA(1, 1), a1 + hstepA, voffA);
;             PG8_WAIT_V(8); PG8_WAIT_L(0); PG8_BAR; PG8_MMA(0, 0, At, B0); PG8_MMA(0, 1, At, B1); PG8_BAR; PG8_SCHED;
;             PG8_LDA(At, 0, 1); PG8_STAGE(PG8_SB(0, 0), b2, voffB); PG8_STAGE(PG8_SB(0, 1), b2 + hstepB, voffB); PG8_STAGE(PG8_SA(0, 0), a2, voffA);
;             PG8_WAIT_V(8); PG8_WAIT_L(0); PG8_BAR; PG8_MMA(1, 0, At, B0); PG8_MMA(1, 1, At, B1); PG8_BAR; PG8_SCHED;
;             PG8_LDB(B0, 1, 0); PG8_LDB(B1, 1, 1); PG8_SCHED; PG8_LDA(At, 1, 0); PG8_STAGE(PG8_SA(0, 1), a2 + hstepA, voffA);
;             PG8_WAIT_V(8); PG8_WAIT_L(0); PG8_BAR; PG8_MMA(0, 0, At, B0); PG8_MMA(0, 1, At, B1); PG8_BAR; PG8_SCHED;
;             PG8_LDA(At, 1, 1); PG8_STAGE(PG8_SB(1, 0), b3, voffB); PG8_STAGE(PG8_SB(1, 1), b3 + hstepB, voffB); PG8_STAGE(PG8_SA(1, 0), a3, voffA);
;             PG8_WAIT_V(8); PG8_WAIT_L(0); PG8_BAR; PG8_MMA(1, 0, At, B0); PG8_MMA(1, 1, At, B1); PG8_BAR; PG8_SCHED;
;         }
.LBB0_310:
	s_add_i32 s72, s40, 2
	s_add_u32 s4, s0, 0x80
	s_addc_u32 s5, s1, 0
	s_add_i32 s73, 0, 0x10000
	s_cmp_eq_u32 s60, s40
	s_cselect_b32 s41, s69, s5
	s_cselect_b32 s40, s68, s4
	v_add_u32_e32 v144, s73, v170
	s_cselect_b32 s43, s71, s75
	s_cselect_b32 s42, s70, s67
	s_add_i32 s4, 0, 0x14000
	ds_read_b128 v[128:131], v144
	ds_read_b128 v[132:135], v144 offset:1024
	ds_read_b128 v[146:149], v144 offset:2048
	ds_read_b128 v[158:161], v144 offset:3072
	v_add_u32_e32 v144, s4, v170
	ds_read_b128 v[162:165], v144
	ds_read_b128 v[166:169], v144 offset:1024
	ds_read_b128 v[174:177], v144 offset:2048
	ds_read_b128 v[178:181], v144 offset:3072
	v_lshl_add_u64 v[218:219], s[0:1], 0, v[156:157]
	s_add_i32 m0, s89, 0xc000
	ds_read_b128 v[182:185], v172
	ds_read_b128 v[186:189], v172 offset:1024
	ds_read_b128 v[190:193], v172 offset:2048
	ds_read_b128 v[194:197], v172 offset:3072
	ds_read_b128 v[198:201], v172 offset:4096
	ds_read_b128 v[206:209], v172 offset:5120
	ds_read_b128 v[210:213], v172 offset:6144
	ds_read_b128 v[214:217], v172 offset:7168
	global_load_lds_dwordx4 v[218:219], off
	v_lshl_add_u64 v[218:219], s[0:1], 0, v[154:155]
	s_add_i32 m0, s89, 0xe000
	s_nop 0
	global_load_lds_dwordx4 v[218:219], off
	s_waitcnt vmcnt(8)
	s_barrier
	s_setprio 1
	s_waitcnt lgkmcnt(7)
	v_mfma_f32_16x16x32_bf16 v[124:127], v[128:131], v[182:185], v[124:127]
	v_mfma_f32_16x16x32_bf16 v[120:123], v[146:149], v[182:185], v[120:123]
	s_waitcnt lgkmcnt(5)
	v_mfma_f32_16x16x32_bf16 v[108:111], v[128:131], v[190:193], v[108:111]
	v_mfma_f32_16x16x32_bf16 v[104:107], v[146:149], v[190:193], v[104:107]
	s_waitcnt lgkmcnt(3)
	v_mfma_f32_16x16x32_bf16 v[92:95], v[128:131], v[198:201], v[92:95]
	v_mfma_f32_16x16x32_bf16 v[88:91], v[146:149], v[198:201], v[88:91]
	s_waitcnt lgkmcnt(1)
	v_mfma_f32_16x16x32_bf16 v[76:79], v[128:131], v[210:213], v[76:79]
	v_mfma_f32_16x16x32_bf16 v[72:75], v[146:149], v[210:213], v[72:75]
	v_mfma_f32_16x16x32_bf16 v[124:127], v[132:135], v[186:189], v[124:127]
	v_mfma_f32_16x16x32_bf16 v[120:123], v[158:161], v[186:189], v[120:123]
	v_mfma_f32_16x16x32_bf16 v[108:111], v[132:135], v[194:197], v[108:111]
	v_mfma_f32_16x16x32_bf16 v[104:107], v[158:161], v[194:197], v[104:107]
	v_mfma_f32_16x16x32_bf16 v[92:95], v[132:135], v[206:209], v[92:95]
	v_mfma_f32_16x16x32_bf16 v[88:91], v[158:161], v[206:209], v[88:91]
	s_waitcnt lgkmcnt(0)
	v_mfma_f32_16x16x32_bf16 v[76:79], v[132:135], v[214:217], v[76:79]
	v_mfma_f32_16x16x32_bf16 v[72:75], v[158:161], v[214:217], v[72:75]
	s_setprio 0
	s_setprio 1
	v_mfma_f32_16x16x32_bf16 v[116:119], v[162:165], v[182:185], v[116:119]
	v_mfma_f32_16x16x32_bf16 v[112:115], v[174:177], v[182:185], v[112:115]
	v_mfma_f32_16x16x32_bf16 v[100:103], v[162:165], v[190:193], v[100:103]
	v_mfma_f32_16x16x32_bf16 v[96:99], v[174:177], v[190:193], v[96:99]
	v_mfma_f32_16x16x32_bf16 v[84:87], v[162:165], v[198:201], v[84:87]
	v_mfma_f32_16x16x32_bf16 v[80:83], v[174:177], v[198:201], v[80:83]
	v_mfma_f32_16x16x32_bf16 v[68:71], v[162:165], v[210:213], v[68:71]
	v_mfma_f32_16x16x32_bf16 v[64:67], v[174:177], v[210:213], v[64:67]
	v_mfma_f32_16x16x32_bf16 v[116:119], v[166:169], v[186:189], v[116:119]
	v_mfma_f32_16x16x32_bf16 v[112:115], v[178:181], v[186:189], v[112:115]
	v_mfma_f32_16x16x32_bf16 v[100:103], v[166:169], v[194:197], v[100:103]
	v_mfma_f32_16x16x32_bf16 v[96:99], v[178:181], v[194:197], v[96:99]
	v_mfma_f32_16x16x32_bf16 v[84:87], v[166:169], v[206:209], v[84:87]
	v_mfma_f32_16x16x32_bf16 v[80:83], v[178:181], v[206:209], v[80:83]
	v_mfma_f32_16x16x32_bf16 v[68:71], v[166:169], v[214:217], v[68:71]
	v_mfma_f32_16x16x32_bf16 v[64:67], v[178:181], v[214:217], v[64:67]
	s_setprio 0
	s_barrier
	s_add_i32 s5, s73, s88
	v_lshl_add_u64 v[218:219], s[42:43], 0, v[138:139]
	s_mov_b32 m0, s5
	ds_read_b128 v[182:185], v172 offset:16384
	ds_read_b128 v[186:189], v172 offset:17408
	ds_read_b128 v[190:193], v172 offset:18432
	ds_read_b128 v[194:197], v172 offset:19456
	ds_read_b128 v[198:201], v172 offset:20480
	ds_read_b128 v[206:209], v172 offset:21504
	ds_read_b128 v[210:213], v172 offset:22528
	ds_read_b128 v[214:217], v172 offset:23552
	global_load_lds_dwordx4 v[218:219], off
	s_add_i32 m0, s5, 0x2000
	v_lshl_add_u64 v[220:221], s[42:43], 0, v[142:143]
	s_add_u32 s42, s42, s99
	s_addc_u32 s43, s43, 0
	s_add_i32 s4, s4, s88
	global_load_lds_dwordx4 v[220:221], off
	v_lshl_add_u64 v[222:223], s[42:43], 0, v[138:139]
	s_mov_b32 m0, s4
	v_lshl_add_u64 v[224:225], s[42:43], 0, v[142:143]
	global_load_lds_dwordx4 v[222:223], off
	s_add_i32 m0, s4, 0x2000
	v_lshl_add_u64 v[226:227], s[40:41], 0, v[136:137]
	global_load_lds_dwordx4 v[224:225], off
	s_mov_b32 m0, s89
	v_lshl_add_u64 v[228:229], s[40:41], 0, v[140:141]
	global_load_lds_dwordx4 v[226:227], off
	s_mov_b32 m0, s90
	s_nop 0
	global_load_lds_dwordx4 v[228:229], off
	s_waitcnt vmcnt(8)
	s_barrier
; #define PG8_STAGE(bufoff, gbase, voff) do { _Pragma("unroll") for (int _i = 0; _i < 2; ++_i) \
;         __builtin_amdgcn_global_load_lds((const unsigned*)((const char*)(gbase) + (voff)[_i]), (LAS unsigned*)(lds + (bufoff) + ldsw + _i * 8192), 16, 0, 0); } while (0)
; #define PG8_LDA(dst, b, h) do { _Pragma("unroll") for (int m = 0; m < 4; ++m) _Pragma("unroll") for (int k = 0; k < 2; ++k) dst[m][k] = *(const LAS bf16x8*)(lds + PG8_SA(b, h) + aoff + m * 2048 + k * 1024); } while (0)
; #define PG8_LDB(dst, b, h) do { _Pragma("unroll") for (int n = 0; n < 2; ++n) _Pragma("unroll") for (int k = 0; k < 2; ++k) dst[n][k] = *(const LAS bf16x8*)(lds + PG8_SB(b, h) + boff + n * 2048 + k * 1024); } while (0)
; #define PG8_WAIT_V(n) asm volatile("s_waitcnt vmcnt(" #n ")" ::: "memory")
; #define PG8_WAIT_L(n) asm volatile("s_waitcnt lgkmcnt(" #n ")" ::: "memory")
; __device__ __forceinline__ void gemm_phase(LAS unsigned char* lds, const Desc& g, int G, int cidx, int tid) {
;     ...
;         for (int t = 0; t < nt; t += 2) {
;             const bool last = (t == nt - 2);
;             const char* a1 = cA + (size_t)(t + 1) * kstep;
;             const char* a2 = last ? nA : cA + (size_t)(t + 2) * kstep; const char* b2 = last ? nB : cB + (size_t)(t + 2) * kstep;
;             const char* a3 = a2 + kstep; const char* b3 = b2 + kstep;
;             PG8_LDB(B0, 0, 0); PG8_LDB(B1, 0, 1); PG8_SCHED; PG8_LDA(At, 0, 0); PG8_STAGE(PG8_SA(1, 1), a1 + hstepA, voffA);
;             PG8_WAIT_V(8); PG8_WAIT_L(0); PG8_BAR; PG8_MMA(0, 0, At, B0); PG8_MMA(0, 1, At, B1); PG8_BAR; PG8_SCHED;
;             PG8_LDA(At, 0, 1); PG8_STAGE(PG8_SB(0, 0), b2, voffB); PG8_STAGE(PG8_SB(0, 1), b2 + hstepB, voffB); PG8_STAGE(PG8_SA(0, 0), a2, voffA);
;             PG8_WAIT_V(8); PG8_WAIT_L(0); PG8_BAR; PG8_MMA(1, 0, At, B0); PG8_MMA(1, 1, At, B1); PG8_BAR; PG8_SCHED;
;             PG8_LDB(B0, 1, 0); PG8_LDB(B1, 1, 1); PG8_SCHED; PG8_LDA(At, 1, 0); PG8_STAGE(PG8_SA(0, 1), a2 + hstepA, voffA);
;             PG8_WAIT_V(8); PG8_WAIT_L(0); PG8_BAR; PG8_MMA(0, 0, At, B0); PG8_MMA(0, 1, At, B1); PG8_BAR; PG8_SCHED;
;             PG8_LDA(At, 1, 1); PG8_STAGE(PG8_SB(1, 0), b3, voffB); PG8_STAGE(PG8_SB(1, 1), b3 + hstepB, voffB); PG8_STAGE(PG8_SA(1, 0), a3, voffA);
;             PG8_WAIT_V(8); PG8_WAIT_L(0); PG8_BAR; PG8_MMA(1, 0, At, B0); PG8_MMA(1, 1, At, B1); PG8_BAR; PG8_SCHED;
;         }
	s_setprio 1
	s_waitcnt lgkmcnt(7)
	v_mfma_f32_16x16x32_bf16 v[60:63], v[128:131], v[182:185], v[60:63]
	v_mfma_f32_16x16x32_bf16 v[56:59], v[146:149], v[182:185], v[56:59]
	s_waitcnt lgkmcnt(5)
	v_mfma_f32_16x16x32_bf16 v[44:47], v[128:131], v[190:193], v[44:47]
	v_mfma_f32_16x16x32_bf16 v[40:43], v[146:149], v[190:193], v[40:43]
	s_waitcnt lgkmcnt(3)
	v_mfma_f32_16x16x32_bf16 v[28:31], v[128:131], v[198:201], v[28:31]
	v_mfma_f32_16x16x32_bf16 v[24:27], v[146:149], v[198:201], v[24:27]
	s_waitcnt lgkmcnt(1)
	v_mfma_f32_16x16x32_bf16 v[12:15], v[128:131], v[210:213], v[12:15]
	v_mfma_f32_16x16x32_bf16 v[8:11], v[146:149], v[210:213], v[8:11]
	v_mfma_f32_16x16x32_bf16 v[60:63], v[132:135], v[186:189], v[60:63]
	v_mfma_f32_16x16x32_bf16 v[56:59], v[158:161], v[186:189], v[56:59]
	v_mfma_f32_16x16x32_bf16 v[44:47], v[132:135], v[194:197], v[44:47]
	v_mfma_f32_16x16x32_bf16 v[40:43], v[158:161], v[194:197], v[40:43]
	v_mfma_f32_16x16x32_bf16 v[28:31], v[132:135], v[206:209], v[28:31]
	v_mfma_f32_16x16x32_bf16 v[24:27], v[158:161], v[206:209], v[24:27]
	s_waitcnt lgkmcnt(0)
	v_mfma_f32_16x16x32_bf16 v[12:15], v[132:135], v[214:217], v[12:15]
	v_mfma_f32_16x16x32_bf16 v[8:11], v[158:161], v[214:217], v[8:11]
	s_setprio 0
	s_setprio 1
	v_mfma_f32_16x16x32_bf16 v[52:55], v[162:165], v[182:185], v[52:55]
	v_mfma_f32_16x16x32_bf16 v[48:51], v[174:177], v[182:185], v[48:51]
	v_mfma_f32_16x16x32_bf16 v[36:39], v[162:165], v[190:193], v[36:39]
	v_mfma_f32_16x16x32_bf16 v[32:35], v[174:177], v[190:193], v[32:35]
	v_mfma_f32_16x16x32_bf16 v[20:23], v[162:165], v[198:201], v[20:23]
	v_mfma_f32_16x16x32_bf16 v[16:19], v[174:177], v[198:201], v[16:19]
	v_mfma_f32_16x16x32_bf16 v[0:3], v[162:165], v[210:213], v[0:3]
	v_mfma_f32_16x16x32_bf16 v[4:7], v[174:177], v[210:213], v[4:7]
	v_mfma_f32_16x16x32_bf16 v[52:55], v[166:169], v[186:189], v[52:55]
	v_mfma_f32_16x16x32_bf16 v[48:51], v[178:181], v[186:189], v[48:51]
	v_mfma_f32_16x16x32_bf16 v[36:39], v[166:169], v[194:197], v[36:39]
	v_mfma_f32_16x16x32_bf16 v[32:35], v[178:181], v[194:197], v[32:35]
	v_mfma_f32_16x16x32_bf16 v[20:23], v[166:169], v[206:209], v[20:23]
	v_mfma_f32_16x16x32_bf16 v[16:19], v[178:181], v[206:209], v[16:19]
	v_mfma_f32_16x16x32_bf16 v[0:3], v[166:169], v[214:217], v[0:3]
	v_mfma_f32_16x16x32_bf16 v[4:7], v[178:181], v[214:217], v[4:7]
	s_setprio 0
	s_barrier
	s_add_i32 s4, 0, 0x18000
	v_add_u32_e32 v144, s4, v170
	s_add_i32 s5, 0, 0x1c000
	ds_read_b128 v[128:131], v144
	ds_read_b128 v[132:135], v144 offset:1024
	ds_read_b128 v[146:149], v144 offset:2048
	ds_read_b128 v[158:161], v144 offset:3072
	v_add_u32_e32 v144, s5, v170
	ds_read_b128 v[162:165], v144
	ds_read_b128 v[166:169], v144 offset:1024
	ds_read_b128 v[174:177], v144 offset:2048
	ds_read_b128 v[178:181], v144 offset:3072
	s_add_u32 s40, s40, s2
	s_addc_u32 s41, s41, 0
	s_mov_b32 m0, s91
	v_lshl_add_u64 v[230:231], s[40:41], 0, v[136:137]
	ds_read_b128 v[182:185], v172 offset:32768
	ds_read_b128 v[186:189], v172 offset:33792
	ds_read_b128 v[190:193], v172 offset:34816
	ds_read_b128 v[194:197], v172 offset:35840
	ds_read_b128 v[198:201], v172 offset:36864
	ds_read_b128 v[206:209], v172 offset:37888
	ds_read_b128 v[210:213], v172 offset:38912
	ds_read_b128 v[214:217], v172 offset:39936
	global_load_lds_dwordx4 v[230:231], off
	v_lshl_add_u64 v[230:231], s[40:41], 0, v[140:141]
	s_mov_b32 m0, s92
	s_nop 0
	global_load_lds_dwordx4 v[230:231], off
	s_waitcnt vmcnt(8)
	s_barrier
	s_setprio 1
	s_waitcnt lgkmcnt(7)
	v_mfma_f32_16x16x32_bf16 v[124:127], v[128:131], v[182:185], v[124:127]
	v_mfma_f32_16x16x32_bf16 v[120:123], v[146:149], v[182:185], v[120:123]
	s_waitcnt lgkmcnt(5)
	v_mfma_f32_16x16x32_bf16 v[108:111], v[128:131], v[190:193], v[108:111]
	v_mfma_f32_16x16x32_bf16 v[104:107], v[146:149], v[190:193], v[104:107]
	s_waitcnt lgkmcnt(3)
	v_mfma_f32_16x16x32_bf16 v[92:95], v[128:131], v[198:201], v[92:95]
	v_mfma_f32_16x16x32_bf16 v[88:91], v[146:149], v[198:201], v[88:91]
	s_waitcnt lgkmcnt(1)
	v_mfma_f32_16x16x32_bf16 v[76:79], v[128:131], v[210:213], v[76:79]
	v_mfma_f32_16x16x32_bf16 v[72:75], v[146:149], v[210:213], v[72:75]
	v_mfma_f32_16x16x32_bf16 v[124:127], v[132:135], v[186:189], v[124:127]
	v_mfma_f32_16x16x32_bf16 v[120:123], v[158:161], v[186:189], v[120:123]
	v_mfma_f32_16x16x32_bf16 v[108:111], v[132:135], v[194:197], v[108:111]
	v_mfma_f32_16x16x32_bf16 v[104:107], v[158:161], v[194:197], v[104:107]
	v_mfma_f32_16x16x32_bf16 v[92:95], v[132:135], v[206:209], v[92:95]
	v_mfma_f32_16x16x32_bf16 v[88:91], v[158:161], v[206:209], v[88:91]
	s_waitcnt lgkmcnt(0)
	v_mfma_f32_16x16x32_bf16 v[76:79], v[132:135], v[214:217], v[76:79]
	v_mfma_f32_16x16x32_bf16 v[72:75], v[158:161], v[214:217], v[72:75]
	s_setprio 0
	s_setprio 1
	v_mfma_f32_16x16x32_bf16 v[116:119], v[162:165], v[182:185], v[116:119]
	v_mfma_f32_16x16x32_bf16 v[112:115], v[174:177], v[182:185], v[112:115]
	v_mfma_f32_16x16x32_bf16 v[100:103], v[162:165], v[190:193], v[100:103]
	v_mfma_f32_16x16x32_bf16 v[96:99], v[174:177], v[190:193], v[96:99]
	v_mfma_f32_16x16x32_bf16 v[84:87], v[162:165], v[198:201], v[84:87]
	v_mfma_f32_16x16x32_bf16 v[80:83], v[174:177], v[198:201], v[80:83]
	v_mfma_f32_16x16x32_bf16 v[68:71], v[162:165], v[210:213], v[68:71]
	v_mfma_f32_16x16x32_bf16 v[64:67], v[174:177], v[210:213], v[64:67]
	v_mfma_f32_16x16x32_bf16 v[116:119], v[166:169], v[186:189], v[116:119]
	v_mfma_f32_16x16x32_bf16 v[112:115], v[178:181], v[186:189], v[112:115]
	v_mfma_f32_16x16x32_bf16 v[100:103], v[166:169], v[194:197], v[100:103]
	v_mfma_f32_16x16x32_bf16 v[96:99], v[178:181], v[194:197], v[96:99]
	v_mfma_f32_16x16x32_bf16 v[84:87], v[166:169], v[206:209], v[84:87]
	v_mfma_f32_16x16x32_bf16 v[80:83], v[178:181], v[206:209], v[80:83]
	v_mfma_f32_16x16x32_bf16 v[68:71], v[166:169], v[214:217], v[68:71]
	v_mfma_f32_16x16x32_bf16 v[64:67], v[178:181], v[214:217], v[64:67]
	s_setprio 0
	s_barrier
; #define PG8_STAGE(bufoff, gbase, voff) do { _Pragma("unroll") for (int _i = 0; _i < 2; ++_i) \
;         __builtin_amdgcn_global_load_lds((const unsigned*)((const char*)(gbase) + (voff)[_i]), (LAS unsigned*)(lds + (bufoff) + ldsw + _i * 8192), 16, 0, 0); } while (0)
; #define PG8_LDA(dst, b, h) do { _Pragma("unroll") for (int m = 0; m < 4; ++m) _Pragma("unroll") for (int k = 0; k < 2; ++k) dst[m][k] = *(const LAS bf16x8*)(lds + PG8_SA(b, h) + aoff + m * 2048 + k * 1024); } while (0)
; #define PG8_LDB(dst, b, h) do { _Pragma("unroll") for (int n = 0; n < 2; ++n) _Pragma("unroll") for (int k = 0; k < 2; ++k) dst[n][k] = *(const LAS bf16x8*)(lds + PG8_SB(b, h) + boff + n * 2048 + k * 1024); } while (0)
; #define PG8_WAIT_V(n) asm volatile("s_waitcnt vmcnt(" #n ")" ::: "memory")
; #define PG8_WAIT_L(n) asm volatile("s_waitcnt lgkmcnt(" #n ")" ::: "memory")
; __device__ __forceinline__ void gemm_phase(LAS unsigned char* lds, const Desc& g, int G, int cidx, int tid) {
;     ...
;         for (int t = 0; t < nt; t += 2) {
;             const bool last = (t == nt - 2);
;             const char* a1 = cA + (size_t)(t + 1) * kstep;
;             const char* a2 = last ? nA : cA + (size_t)(t + 2) * kstep; const char* b2 = last ? nB : cB + (size_t)(t + 2) * kstep;
;             const char* a3 = a2 + kstep; const char* b3 = b2 + kstep;
;             PG8_LDB(B0, 0, 0); PG8_LDB(B1, 0, 1); PG8_SCHED; PG8_LDA(At, 0, 0); PG8_STAGE(PG8_SA(1, 1), a1 + hstepA, voffA);
;             PG8_WAIT_V(8); PG8_WAIT_L(0); PG8_BAR; PG8_MMA(0, 0, At, B0); PG8_MMA(0, 1, At, B1); PG8_BAR; PG8_SCHED;
;             PG8_LDA(At, 0, 1); PG8_STAGE(PG8_SB(0, 0), b2, voffB); PG8_STAGE(PG8_SB(0, 1), b2 + hstepB, voffB); PG8_STAGE(PG8_SA(0, 0), a2, voffA);
;             PG8_WAIT_V(8); PG8_WAIT_L(0); PG8_BAR; PG8_MMA(1, 0, At, B0); PG8_MMA(1, 1, At, B1); PG8_BAR; PG8_SCHED;
;             PG8_LDB(B0, 1, 0); PG8_LDB(B1, 1, 1); PG8_SCHED; PG8_LDA(At, 1, 0); PG8_STAGE(PG8_SA(0, 1), a2 + hstepA, voffA);
;             PG8_WAIT_V(8); PG8_WAIT_L(0); PG8_BAR; PG8_MMA(0, 0, At, B0); PG8_MMA(0, 1, At, B1); PG8_BAR; PG8_SCHED;
;             PG8_LDA(At, 1, 1); PG8_STAGE(PG8_SB(1, 0), b3, voffB); PG8_STAGE(PG8_SB(1, 1), b3 + hstepB, voffB); PG8_STAGE(PG8_SA(1, 0), a3, voffA);
;             PG8_WAIT_V(8); PG8_WAIT_L(0); PG8_BAR; PG8_MMA(1, 0, At, B0); PG8_MMA(1, 1, At, B1); PG8_BAR; PG8_SCHED;
;         }
	s_add_i32 s4, s4, s88
	v_lshl_add_u64 v[218:219], v[218:219], 0, s[22:23]
	s_mov_b32 m0, s4
	ds_read_b128 v[182:185], v172 offset:49152
	ds_read_b128 v[186:189], v172 offset:50176
	ds_read_b128 v[190:193], v172 offset:51200
	ds_read_b128 v[194:197], v172 offset:52224
	ds_read_b128 v[198:201], v172 offset:53248
	ds_read_b128 v[206:209], v172 offset:54272
	ds_read_b128 v[210:213], v172 offset:55296
	ds_read_b128 v[214:217], v172 offset:56320
	global_load_lds_dwordx4 v[218:219], off
	v_lshl_add_u64 v[218:219], v[220:221], 0, s[22:23]
	s_add_i32 m0, s4, 0x2000
	s_add_i32 s4, s5, s88
	global_load_lds_dwordx4 v[218:219], off
	v_lshl_add_u64 v[218:219], v[222:223], 0, s[22:23]
	s_mov_b32 m0, s4
	s_nop 0
	global_load_lds_dwordx4 v[218:219], off
	v_lshl_add_u64 v[218:219], v[224:225], 0, s[22:23]
	s_add_i32 m0, s4, 0x2000
	s_nop 0
	global_load_lds_dwordx4 v[218:219], off
	v_lshl_add_u64 v[218:219], v[226:227], 0, s[22:23]
	s_mov_b32 m0, s54
	s_nop 0
	global_load_lds_dwordx4 v[218:219], off
	v_lshl_add_u64 v[218:219], v[228:229], 0, s[22:23]
	s_mov_b32 m0, s55
	s_nop 0
	global_load_lds_dwordx4 v[218:219], off
	s_waitcnt vmcnt(8)
	s_barrier
	s_setprio 1
	s_waitcnt lgkmcnt(7)
	v_mfma_f32_16x16x32_bf16 v[60:63], v[128:131], v[182:185], v[60:63]
	v_mfma_f32_16x16x32_bf16 v[56:59], v[146:149], v[182:185], v[56:59]
	s_waitcnt lgkmcnt(5)
	v_mfma_f32_16x16x32_bf16 v[44:47], v[128:131], v[190:193], v[44:47]
	v_mfma_f32_16x16x32_bf16 v[40:43], v[146:149], v[190:193], v[40:43]
	s_waitcnt lgkmcnt(3)
	v_mfma_f32_16x16x32_bf16 v[28:31], v[128:131], v[198:201], v[28:31]
	v_mfma_f32_16x16x32_bf16 v[24:27], v[146:149], v[198:201], v[24:27]
	s_waitcnt lgkmcnt(1)
	v_mfma_f32_16x16x32_bf16 v[12:15], v[128:131], v[210:213], v[12:15]
	v_mfma_f32_16x16x32_bf16 v[8:11], v[146:149], v[210:213], v[8:11]
	v_mfma_f32_16x16x32_bf16 v[60:63], v[132:135], v[186:189], v[60:63]
	v_mfma_f32_16x16x32_bf16 v[56:59], v[158:161], v[186:189], v[56:59]
	v_mfma_f32_16x16x32_bf16 v[44:47], v[132:135], v[194:197], v[44:47]
	v_mfma_f32_16x16x32_bf16 v[40:43], v[158:161], v[194:197], v[40:43]
	v_mfma_f32_16x16x32_bf16 v[28:31], v[132:135], v[206:209], v[28:31]
	v_mfma_f32_16x16x32_bf16 v[24:27], v[158:161], v[206:209], v[24:27]
	s_waitcnt lgkmcnt(0)
	v_mfma_f32_16x16x32_bf16 v[12:15], v[132:135], v[214:217], v[12:15]
	v_mfma_f32_16x16x32_bf16 v[8:11], v[158:161], v[214:217], v[8:11]
	s_setprio 0
	s_setprio 1
	v_mfma_f32_16x16x32_bf16 v[52:55], v[162:165], v[182:185], v[52:55]
	v_mfma_f32_16x16x32_bf16 v[48:51], v[174:177], v[182:185], v[48:51]
	v_mfma_f32_16x16x32_bf16 v[36:39], v[162:165], v[190:193], v[36:39]
	v_mfma_f32_16x16x32_bf16 v[32:35], v[174:177], v[190:193], v[32:35]
	v_mfma_f32_16x16x32_bf16 v[20:23], v[162:165], v[198:201], v[20:23]
	v_mfma_f32_16x16x32_bf16 v[16:19], v[174:177], v[198:201], v[16:19]
	v_mfma_f32_16x16x32_bf16 v[0:3], v[162:165], v[210:213], v[0:3]
	v_mfma_f32_16x16x32_bf16 v[4:7], v[174:177], v[210:213], v[4:7]
	v_mfma_f32_16x16x32_bf16 v[52:55], v[166:169], v[186:189], v[52:55]
	v_mfma_f32_16x16x32_bf16 v[48:51], v[178:181], v[186:189], v[48:51]
	v_mfma_f32_16x16x32_bf16 v[36:39], v[166:169], v[194:197], v[36:39]
	v_mfma_f32_16x16x32_bf16 v[32:35], v[178:181], v[194:197], v[32:35]
	v_mfma_f32_16x16x32_bf16 v[20:23], v[166:169], v[206:209], v[20:23]
	v_mfma_f32_16x16x32_bf16 v[16:19], v[178:181], v[206:209], v[16:19]
	v_mfma_f32_16x16x32_bf16 v[0:3], v[166:169], v[214:217], v[0:3]
	v_mfma_f32_16x16x32_bf16 v[4:7], v[178:181], v[214:217], v[4:7]
	s_setprio 0
	s_barrier
	s_add_u32 s67, s67, 0x100
	s_addc_u32 s75, s75, 0
	s_add_u32 s0, s0, 0x100
	s_addc_u32 s1, s1, 0
	s_cmp_ge_u32 s72, s6
	s_mov_b32 s40, s72
	s_cbranch_scc0 .LBB0_310
	s_and_b64 vcc, exec, s[8:9]
	s_cbranch_vccz .LBB0_313
	s_barrier
